# attention: second-half softmax (exp/sum/cvt of keys 32-63) interleaved into first-half PV MFMAs; P fragments in v240-255, l in v239
# baseline (speedup 1.0000x reference)
.LBB0_509:
	s_xor_b64 s[18:19], s[4:5], -1
	s_lshl_b64 s[4:5], s[0:1], 1
	s_add_u32 s22, s56, s4
	s_addc_u32 s23, s57, s5
	v_mov_b32_e32 v2, v208
	s_add_u32 s0, s58, s4
	s_addc_u32 s1, s59, s5
	v_readfirstlane_b32 s20, v2
	s_ashr_i32 s24, s20, 6
	s_and_b32 s20, s20, 0x3fffffc0
	s_lshl_b32 s20, s20, 2
	v_and_b32_e32 v219, 31, v2
	s_add_i32 s21, s20, 0
	s_lshl_b32 s20, s24, 5
	v_or_b32_e32 v0, s20, v219
	s_waitcnt lgkmcnt(0)
	v_ashrrev_i32_e32 v1, 31, v0
	v_bfe_u32 v218, v2, 5, 1
	v_lshlrev_b64 v[0:1], 11, v[0:1]
	v_lshl_add_u64 v[0:1], s[22:23], 0, v[0:1]
	v_lshlrev_b32_e32 v210, 4, v218
	v_lshl_add_u64 v[0:1], v[0:1], 0, v[210:211]
	global_load_dwordx4 v[160:163], v[0:1], off
	global_load_dwordx4 v[164:167], v[0:1], off offset:32
	global_load_dwordx4 v[168:171], v[0:1], off offset:64
	global_load_dwordx4 v[172:175], v[0:1], off offset:96
	global_load_dwordx4 v[176:179], v[0:1], off offset:128
	global_load_dwordx4 v[180:183], v[0:1], off offset:160
	global_load_dwordx4 v[184:187], v[0:1], off offset:192
	global_load_dwordx4 v[188:191], v[0:1], off offset:224
	s_lshl_b32 s22, s24, 3
	v_bfe_u32 v1, v2, 4, 2
	v_or_b32_e32 v0, s22, v1
	v_bitop3_b32 v4, v1, v2, 15 bitop3:0x78
	v_ashrrev_i32_e32 v1, 31, v0
	v_lshlrev_b64 v[212:213], 10, v[0:1]
	v_or_b32_e32 v0, 4, v0
	v_and_b32_e32 v3, 15, v2
	v_ashrrev_i32_e32 v1, 31, v0
	v_bitop3_b32 v3, v0, v3, 7 bitop3:0x6c
	s_and_b32 s25, s24, 1
	s_lshl_b32 s25, s25, 3
	v_xor_b32_e32 v4, s25, v4
	v_xor_b32_e32 v3, s25, v3
	v_lshlrev_b64 v[214:215], 10, v[0:1]
	v_bfe_u32 v0, v2, 2, 3
	v_bitop3_b32 v0, s22, -13, v0 bitop3:0xc8
	v_lshrrev_b32_e32 v1, 2, v2
	s_lshl_b32 s22, s24, 3
	v_and_b32_e32 v1, 4, v1
	s_and_b32 s22, s22, 8
	v_or3_b32 v0, v0, v1, s22
	s_add_i32 s21, s21, 0x24000
	v_ashrrev_i32_e32 v1, 31, v0
	v_lshlrev_b32_e32 v11, 3, v2
	s_lshl_b32 s22, s24, 11
	v_lshl_or_b32 v212, v4, 3, v212
	v_lshlrev_b64 v[216:217], 10, v[0:1]
	v_and_b32_e32 v0, 32, v2
	v_and_b32_e32 v1, 24, v11
	s_cmp_lg_u32 0, -1
	v_or3_b32 v216, v216, v1, v0
	v_lshlrev_b64 v[0:1], 1, v[212:213]
	s_cselect_b32 s23, 0, 0
	v_and_b32_e32 v10, 63, v2
	v_lshl_or_b32 v214, v3, 3, v214
	v_lshlrev_b32_e32 v12, 4, v2
	v_lshlrev_b32_e32 v13, 1, v2
	v_lshl_add_u64 v[2:3], s[0:1], 0, v[0:1]
	s_add_i32 s75, s22, s23
	s_mov_b32 s25, m0
	s_mov_b32 m0, s75
	s_nop 0
	global_load_lds_dwordx4 v[2:3], off
	s_mov_b32 m0, s25
	v_lshlrev_b64 v[2:3], 1, v[214:215]
	s_or_b32 s25, s22, 0x400
	v_lshl_add_u64 v[4:5], s[0:1], 0, v[2:3]
	s_add_i32 s77, s25, s23
	s_mov_b32 s84, m0
	s_mov_b32 m0, s77
	s_nop 0
	global_load_lds_dwordx4 v[4:5], off
	s_mov_b32 m0, s84
	s_lshl_b32 s24, s24, 12
	v_lshlrev_b64 v[4:5], 1, v[216:217]
	s_add_i32 s84, s23, 0xc000
	v_lshl_add_u64 v[6:7], s[14:15], 0, v[4:5]
	s_add_i32 s77, s24, s84
	s_mov_b32 s85, m0
	s_mov_b32 m0, s77
	s_nop 0
	global_load_lds_dwordx4 v[6:7], off
	s_mov_b32 m0, s85
	s_or_b32 s85, s24, 0x400
	s_add_i32 s86, s85, s84
	v_lshl_add_u64 v[8:9], v[6:7], 0, s[8:9]
	s_mov_b32 s87, m0
	s_mov_b32 m0, s86
	s_nop 0
	global_load_lds_dwordx4 v[8:9], off
	s_mov_b32 m0, s87
	s_or_b32 s86, s24, 0x800
	s_add_i32 s87, s86, s84
	v_lshl_add_u64 v[8:9], v[6:7], 0, s[10:11]
	s_mov_b32 s96, m0
	s_mov_b32 m0, s87
	s_nop 0
	global_load_lds_dwordx4 v[8:9], off
	s_mov_b32 m0, s96
	s_or_b32 s87, s24, 0xc00
	s_add_i32 s96, s87, s84
	s_add_u32 s0, s0, 0x20000
	v_lshl_add_u64 v[6:7], v[6:7], 0, s[12:13]
	s_mov_b32 s97, m0
	s_mov_b32 m0, s96
	s_nop 0
	global_load_lds_dwordx4 v[6:7], off
	s_mov_b32 m0, s97
	s_addc_u32 s1, s1, 0
	s_add_i32 s96, s23, 0x4000
	v_lshl_add_u64 v[0:1], s[0:1], 0, v[0:1]
	s_add_i32 s22, s22, s96
	s_mov_b32 s97, m0
	s_mov_b32 m0, s22
	s_nop 0
	global_load_lds_dwordx4 v[0:1], off
	s_mov_b32 m0, s97
	v_lshl_add_u64 v[0:1], s[0:1], 0, v[2:3]
	s_add_i32 s25, s25, s96
	s_mov_b32 s0, m0
	s_mov_b32 m0, s25
	s_nop 0
	global_load_lds_dwordx4 v[0:1], off
	s_mov_b32 m0, s0
	s_add_i32 s23, s23, 0x14000
	v_lshl_add_u64 v[0:1], s[16:17], 0, v[4:5]
	s_add_i32 s24, s24, s23
	s_mov_b32 s0, m0
	s_mov_b32 m0, s24
	s_nop 0
	global_load_lds_dwordx4 v[0:1], off
	s_mov_b32 m0, s0
	v_lshl_add_u64 v[2:3], v[0:1], 0, s[8:9]
	s_add_i32 s85, s85, s23
	s_mov_b32 s0, m0
	s_mov_b32 m0, s85
	s_nop 0
	global_load_lds_dwordx4 v[2:3], off
	s_mov_b32 m0, s0
	v_lshl_add_u64 v[2:3], v[0:1], 0, s[10:11]
	s_add_i32 s86, s86, s23
	s_mov_b32 s0, m0
	s_mov_b32 m0, s86
	s_nop 0
	global_load_lds_dwordx4 v[2:3], off
	s_mov_b32 m0, s0
	v_lshl_add_u64 v[0:1], v[0:1], 0, s[12:13]
	s_add_i32 s87, s87, s23
	s_mov_b32 s0, m0
	s_mov_b32 m0, s87
	s_nop 0
	global_load_lds_dwordx4 v[0:1], off
	s_mov_b32 m0, s0
	s_movk_i32 s0, 0x70
	v_and_b32_e32 v1, 0x70, v12
	v_bitop3_b32 v221, v210, v12, s0 bitop3:0x78
	s_movk_i32 s0, 0x60
	v_bitop3_b32 v224, v210, v1, s0 bitop3:0x36
	s_movk_i32 s0, 0x80
	v_and_b32_e32 v0, 0x118, v11
	v_bitop3_b32 v225, v210, v1, s0 bitop3:0x36
	s_movk_i32 s0, 0xa0
	v_and_b32_e32 v14, 0xc0, v12
	v_bitop3_b32 v227, v210, v1, s0 bitop3:0x36
	s_movk_i32 s0, 0xc0
	v_and_or_b32 v0, v13, 32, v0
	v_bitop3_b32 v228, v210, v1, s0 bitop3:0x36
	s_movk_i32 s0, 0xe0
	v_add3_u32 v230, v14, s84, v0
	v_mov_b32_e32 v14, v211
	v_mov_b32_e32 v15, v211
	v_bitop3_b32 v222, v210, v1, 32 bitop3:0x36
	v_bitop3_b32 v223, v210, v1, 64 bitop3:0x36
	v_bitop3_b32 v229, v210, v1, s0 bitop3:0x36
	v_and_b32_e32 v236, 0x80, v12
	v_xor_b32_e32 v221, v236, v221
	v_xor_b32_e32 v222, v236, v222
	v_xor_b32_e32 v223, v236, v223
	v_xor_b32_e32 v224, v236, v224
	v_xor_b32_e32 v225, v236, v225
	v_xor_b32_e32 v227, v236, v227
	v_xor_b32_e32 v228, v236, v228
	v_xor_b32_e32 v229, v236, v229
	v_cmp_gt_u32_e64 s[0:1], 32, v10
	s_add_u32 s84, s66, s4
	v_mov_b32_e32 v0, v211
	v_mov_b32_e32 v1, v211
	v_mov_b32_e32 v2, v211
	v_mov_b32_e32 v3, v211
	v_mov_b32_e32 v4, v211
	v_mov_b32_e32 v5, v211
	v_mov_b32_e32 v6, v211
	v_mov_b32_e32 v7, v211
	v_mov_b32_e32 v8, v211
	v_mov_b32_e32 v9, v211
	v_mov_b32_e32 v10, v211
	v_mov_b32_e32 v11, v211
	v_mov_b32_e32 v12, v211
	v_mov_b32_e32 v13, v211
	v_mov_b64_e32 v[126:127], v[14:15]
	v_mov_b64_e32 v[110:111], v[14:15]
	v_mov_b64_e32 v[94:95], v[14:15]
	v_mov_b64_e32 v[78:79], v[14:15]
	v_mov_b64_e32 v[62:63], v[14:15]
	v_mov_b64_e32 v[46:47], v[14:15]
	v_mov_b64_e32 v[30:31], v[14:15]
	s_mov_b32 s74, 2
	s_mov_b32 s76, 0
	v_lshlrev_b32_e32 v220, 8, v219
	v_lshl_add_u32 v226, v219, 2, s21
	s_addc_u32 s85, s67, s5
	v_mov_b32_e32 v232, 0
	v_mov_b32_e32 v239, 0
	v_mov_b32_e32 v231, 0xf149f2ca
	s_mov_b64 s[22:23], 0
	v_mov_b64_e32 v[124:125], v[12:13]
	v_mov_b64_e32 v[122:123], v[10:11]
	v_mov_b64_e32 v[120:121], v[8:9]
	v_mov_b64_e32 v[118:119], v[6:7]
	v_mov_b64_e32 v[116:117], v[4:5]
	v_mov_b64_e32 v[114:115], v[2:3]
	v_mov_b64_e32 v[112:113], v[0:1]
	v_mov_b64_e32 v[108:109], v[12:13]
	v_mov_b64_e32 v[106:107], v[10:11]
	v_mov_b64_e32 v[104:105], v[8:9]
	v_mov_b64_e32 v[102:103], v[6:7]
	v_mov_b64_e32 v[100:101], v[4:5]
	v_mov_b64_e32 v[98:99], v[2:3]
	v_mov_b64_e32 v[96:97], v[0:1]
	v_mov_b64_e32 v[92:93], v[12:13]
	v_mov_b64_e32 v[90:91], v[10:11]
	v_mov_b64_e32 v[88:89], v[8:9]
	v_mov_b64_e32 v[86:87], v[6:7]
	v_mov_b64_e32 v[84:85], v[4:5]
	v_mov_b64_e32 v[82:83], v[2:3]
	v_mov_b64_e32 v[80:81], v[0:1]
	v_mov_b64_e32 v[76:77], v[12:13]
	v_mov_b64_e32 v[74:75], v[10:11]
	v_mov_b64_e32 v[72:73], v[8:9]
	v_mov_b64_e32 v[70:71], v[6:7]
	v_mov_b64_e32 v[68:69], v[4:5]
	v_mov_b64_e32 v[66:67], v[2:3]
	v_mov_b64_e32 v[64:65], v[0:1]
	v_mov_b64_e32 v[60:61], v[12:13]
	v_mov_b64_e32 v[58:59], v[10:11]
	v_mov_b64_e32 v[56:57], v[8:9]
	v_mov_b64_e32 v[54:55], v[6:7]
	v_mov_b64_e32 v[52:53], v[4:5]
	v_mov_b64_e32 v[50:51], v[2:3]
	v_mov_b64_e32 v[48:49], v[0:1]
	v_mov_b64_e32 v[44:45], v[12:13]
	v_mov_b64_e32 v[42:43], v[10:11]
	v_mov_b64_e32 v[40:41], v[8:9]
	v_mov_b64_e32 v[38:39], v[6:7]
	v_mov_b64_e32 v[36:37], v[4:5]
	v_mov_b64_e32 v[34:35], v[2:3]
	v_mov_b64_e32 v[32:33], v[0:1]
	v_mov_b64_e32 v[28:29], v[12:13]
	v_mov_b64_e32 v[26:27], v[10:11]
	v_mov_b64_e32 v[24:25], v[8:9]
	v_mov_b64_e32 v[22:23], v[6:7]
	v_mov_b64_e32 v[20:21], v[4:5]
	v_mov_b64_e32 v[18:19], v[2:3]
	v_mov_b64_e32 v[16:17], v[0:1]
	s_mov_b32 s86, 0
	s_cmp_eq_u32 s22, 0x7e0000
	s_mov_b64 s[4:5], -1
	s_cbranch_scc0 .LBB0_519

.LBB0_517:
	v_cndmask_b32_e64 v231, v234, v231, s[4:5]
	v_mul_f32_e32 v192, 0xbe0293ee, v231
	v_fmamk_f32 v144, v144, 0x3e0293ee, v192
	v_fmamk_f32 v145, v145, 0x3e0293ee, v192
	v_fmamk_f32 v146, v146, 0x3e0293ee, v192
	v_fmamk_f32 v147, v147, 0x3e0293ee, v192
	v_fmamk_f32 v148, v148, 0x3e0293ee, v192
	v_fmamk_f32 v149, v149, 0x3e0293ee, v192
	v_fmamk_f32 v150, v150, 0x3e0293ee, v192
	v_fmamk_f32 v151, v151, 0x3e0293ee, v192
	v_fmamk_f32 v152, v152, 0x3e0293ee, v192
	v_fmamk_f32 v153, v153, 0x3e0293ee, v192
	v_fmamk_f32 v154, v154, 0x3e0293ee, v192
	v_fmamk_f32 v155, v155, 0x3e0293ee, v192
	v_fmamk_f32 v156, v156, 0x3e0293ee, v192
	v_fmamk_f32 v157, v157, 0x3e0293ee, v192
	v_fmamk_f32 v158, v158, 0x3e0293ee, v192
	v_fmamk_f32 v159, v159, 0x3e0293ee, v192
	v_fmamk_f32 v128, v128, 0x3e0293ee, v192
	v_fmamk_f32 v129, v129, 0x3e0293ee, v192
	v_fmamk_f32 v130, v130, 0x3e0293ee, v192
	v_fmamk_f32 v131, v131, 0x3e0293ee, v192
	v_fmamk_f32 v132, v132, 0x3e0293ee, v192
	v_fmamk_f32 v133, v133, 0x3e0293ee, v192
	v_fmamk_f32 v134, v134, 0x3e0293ee, v192
	v_fmamk_f32 v135, v135, 0x3e0293ee, v192
	v_fmamk_f32 v136, v136, 0x3e0293ee, v192
	v_fmamk_f32 v137, v137, 0x3e0293ee, v192
	v_fmamk_f32 v138, v138, 0x3e0293ee, v192
	v_fmamk_f32 v139, v139, 0x3e0293ee, v192
	v_fmamk_f32 v140, v140, 0x3e0293ee, v192
	v_fmamk_f32 v141, v141, 0x3e0293ee, v192
	v_fmamk_f32 v142, v142, 0x3e0293ee, v192
	v_fmamk_f32 v143, v143, 0x3e0293ee, v192
	v_exp_f32_e32 v144, v144
	v_exp_f32_e32 v145, v145
	v_exp_f32_e32 v146, v146
	v_exp_f32_e32 v147, v147
	v_exp_f32_e32 v148, v148
	v_exp_f32_e32 v149, v149
	v_exp_f32_e32 v150, v150
	v_exp_f32_e32 v151, v151
	v_exp_f32_e32 v152, v152
	v_exp_f32_e32 v153, v153
	v_exp_f32_e32 v154, v154
	v_exp_f32_e32 v155, v155
	v_exp_f32_e32 v156, v156
	v_exp_f32_e32 v157, v157
	v_exp_f32_e32 v158, v158
	v_exp_f32_e32 v159, v159
	v_add_f32_e32 v236, v144, v145
	v_add_f32_e32 v236, v146, v236
	v_add_f32_e32 v236, v147, v236
	v_add_f32_e32 v236, v148, v236
	v_add_f32_e32 v236, v149, v236
	v_add_f32_e32 v236, v150, v236
	v_add_f32_e32 v236, v151, v236
	v_add_f32_e32 v236, v152, v236
	v_add_f32_e32 v236, v153, v236
	v_add_f32_e32 v236, v154, v236
	v_add_f32_e32 v236, v155, v236
	v_add_f32_e32 v236, v156, v236
	v_add_f32_e32 v236, v157, v236
	v_add_f32_e32 v236, v158, v236
	v_add_f32_e32 v236, v159, v236
	v_cvt_pk_bf16_f32 v240, v144, v145
	v_cvt_pk_bf16_f32 v241, v146, v147
	v_cvt_pk_bf16_f32 v242, v148, v149
	v_cvt_pk_bf16_f32 v243, v150, v151
	v_cvt_pk_bf16_f32 v244, v152, v153
	v_cvt_pk_bf16_f32 v245, v154, v155
	v_cvt_pk_bf16_f32 v246, v156, v157
	v_cvt_pk_bf16_f32 v247, v158, v159
	v_mov_b32_e32 v158, v233
	v_lshl_add_u32 v145, s76, 15, v230
	ds_read_b64_tr_b16 v[146:147], v145 offset:0
	ds_read_b64_tr_b16 v[148:149], v145 offset:4096
	ds_read_b64_tr_b16 v[150:151], v145 offset:8192
	ds_read_b64_tr_b16 v[152:153], v145 offset:12288
	ds_read_b64_tr_b16 v[154:155], v145 offset:512
	ds_read_b64_tr_b16 v[156:157], v145 offset:4608
	ds_read_b64_tr_b16 v[192:193], v145 offset:8704
	ds_read_b64_tr_b16 v[194:195], v145 offset:12800
	ds_read_b64_tr_b16 v[196:197], v145 offset:1024
	ds_read_b64_tr_b16 v[198:199], v145 offset:5120
	ds_read_b64_tr_b16 v[200:201], v145 offset:9216
	ds_read_b64_tr_b16 v[202:203], v145 offset:13312
	ds_read_b64_tr_b16 v[204:205], v145 offset:1536
	ds_read_b64_tr_b16 v[206:207], v145 offset:5632
	s_waitcnt lgkmcnt(12)
	s_nop 0
	v_mfma_f32_32x32x16_bf16 v[0:15], v[240:243], v[146:149], v[0:15]
	ds_read_b64_tr_b16 v[232:233], v145 offset:9728
	ds_read_b64_tr_b16 v[234:235], v145 offset:13824
	v_exp_f32_e32 v128, v128
	v_exp_f32_e32 v129, v129
	v_exp_f32_e32 v130, v130
	s_waitcnt lgkmcnt(12)
	v_mfma_f32_32x32x16_bf16 v[0:15], v[244:247], v[150:153], v[0:15]
	ds_read_b64_tr_b16 v[146:147], v145 offset:2048
	ds_read_b64_tr_b16 v[148:149], v145 offset:6144
	v_exp_f32_e32 v131, v131
	v_exp_f32_e32 v132, v132
	s_waitcnt lgkmcnt(12)
	v_mfma_f32_32x32x16_bf16 v[112:127], v[240:243], v[154:157], v[112:127]
	ds_read_b64_tr_b16 v[150:151], v145 offset:10240
	ds_read_b64_tr_b16 v[152:153], v145 offset:14336
	v_exp_f32_e32 v133, v133
	v_exp_f32_e32 v134, v134
	v_exp_f32_e32 v135, v135
	s_waitcnt lgkmcnt(12)
	v_mfma_f32_32x32x16_bf16 v[112:127], v[244:247], v[192:195], v[112:127]
	ds_read_b64_tr_b16 v[154:155], v145 offset:2560
	ds_read_b64_tr_b16 v[156:157], v145 offset:6656
	v_exp_f32_e32 v136, v136
	v_exp_f32_e32 v137, v137
	s_waitcnt lgkmcnt(12)
	v_mfma_f32_32x32x16_bf16 v[96:111], v[240:243], v[196:199], v[96:111]
	ds_read_b64_tr_b16 v[192:193], v145 offset:10752
	ds_read_b64_tr_b16 v[194:195], v145 offset:14848
	v_exp_f32_e32 v138, v138
	v_exp_f32_e32 v139, v139
	v_exp_f32_e32 v140, v140
	s_waitcnt lgkmcnt(12)
	v_mfma_f32_32x32x16_bf16 v[96:111], v[244:247], v[200:203], v[96:111]
	ds_read_b64_tr_b16 v[196:197], v145 offset:3072
	ds_read_b64_tr_b16 v[198:199], v145 offset:7168
	v_exp_f32_e32 v141, v141
	v_exp_f32_e32 v142, v142
	s_waitcnt lgkmcnt(12)
	v_mfma_f32_32x32x16_bf16 v[80:95], v[240:243], v[204:207], v[80:95]
	ds_read_b64_tr_b16 v[200:201], v145 offset:11264
	ds_read_b64_tr_b16 v[202:203], v145 offset:15360
	v_exp_f32_e32 v143, v143
	v_add_f32_e32 v236, v128, v236
	v_add_f32_e32 v236, v129, v236
	s_waitcnt lgkmcnt(12)
	v_mfma_f32_32x32x16_bf16 v[80:95], v[244:247], v[232:235], v[80:95]
	ds_read_b64_tr_b16 v[204:205], v145 offset:3584
	ds_read_b64_tr_b16 v[206:207], v145 offset:7680
	v_add_f32_e32 v236, v130, v236
	v_add_f32_e32 v236, v131, v236
	s_waitcnt lgkmcnt(12)
	v_mfma_f32_32x32x16_bf16 v[64:79], v[240:243], v[146:149], v[64:79]
	ds_read_b64_tr_b16 v[232:233], v145 offset:11776
	ds_read_b64_tr_b16 v[234:235], v145 offset:15872
	v_add_f32_e32 v236, v132, v236
	v_add_f32_e32 v236, v133, v236
	v_add_f32_e32 v236, v134, v236
	s_waitcnt lgkmcnt(12)
	v_mfma_f32_32x32x16_bf16 v[64:79], v[244:247], v[150:153], v[64:79]
	ds_read_b64_tr_b16 v[146:147], v145 offset:16384
	ds_read_b64_tr_b16 v[148:149], v145 offset:20480
	v_add_f32_e32 v236, v135, v236
	v_add_f32_e32 v236, v136, v236
	s_waitcnt lgkmcnt(12)
	v_mfma_f32_32x32x16_bf16 v[48:63], v[240:243], v[154:157], v[48:63]
	ds_read_b64_tr_b16 v[150:151], v145 offset:24576
	ds_read_b64_tr_b16 v[152:153], v145 offset:28672
	v_add_f32_e32 v236, v137, v236
	v_add_f32_e32 v236, v138, v236
	v_add_f32_e32 v236, v139, v236
	s_waitcnt lgkmcnt(12)
	v_mfma_f32_32x32x16_bf16 v[48:63], v[244:247], v[192:195], v[48:63]
	ds_read_b64_tr_b16 v[154:155], v145 offset:16896
	ds_read_b64_tr_b16 v[156:157], v145 offset:20992
	v_add_f32_e32 v236, v140, v236
	v_add_f32_e32 v236, v141, v236
	s_waitcnt lgkmcnt(12)
	v_mfma_f32_32x32x16_bf16 v[32:47], v[240:243], v[196:199], v[32:47]
	ds_read_b64_tr_b16 v[192:193], v145 offset:25088
	ds_read_b64_tr_b16 v[194:195], v145 offset:29184
	v_add_f32_e32 v236, v142, v236
	v_add_f32_e32 v236, v143, v236
	v_cvt_pk_bf16_f32 v248, v128, v129
	s_waitcnt lgkmcnt(12)
	v_mfma_f32_32x32x16_bf16 v[32:47], v[244:247], v[200:203], v[32:47]
	ds_read_b64_tr_b16 v[196:197], v145 offset:17408
	ds_read_b64_tr_b16 v[198:199], v145 offset:21504
	v_cvt_pk_bf16_f32 v249, v130, v131
	v_cvt_pk_bf16_f32 v250, v132, v133
	s_waitcnt lgkmcnt(12)
	v_mfma_f32_32x32x16_bf16 v[16:31], v[240:243], v[204:207], v[16:31]
	ds_read_b64_tr_b16 v[200:201], v145 offset:25600
	ds_read_b64_tr_b16 v[202:203], v145 offset:29696
	v_cvt_pk_bf16_f32 v251, v134, v135
	v_cvt_pk_bf16_f32 v252, v136, v137
	v_cvt_pk_bf16_f32 v253, v138, v139
	s_waitcnt lgkmcnt(12)
	v_mfma_f32_32x32x16_bf16 v[16:31], v[244:247], v[232:235], v[16:31]
	ds_read_b64_tr_b16 v[204:205], v145 offset:17920
	ds_read_b64_tr_b16 v[206:207], v145 offset:22016
	v_cvt_pk_bf16_f32 v254, v140, v141
	v_cvt_pk_bf16_f32 v255, v142, v143
	s_waitcnt lgkmcnt(12)
	s_nop 1
	v_mfma_f32_32x32x16_bf16 v[0:15], v[248:251], v[146:149], v[0:15]
	ds_read_b64_tr_b16 v[232:233], v145 offset:26112
	ds_read_b64_tr_b16 v[234:235], v145 offset:30208
	v_mov_b32_e32 v237, v236
	s_nop 1
	v_permlane32_swap_b32_e32 v236, v237
	v_add_f32_e32 v144, v236, v237
	v_fmac_f32_e32 v144, v239, v158
	s_waitcnt lgkmcnt(12)
	v_mfma_f32_32x32x16_bf16 v[0:15], v[252:255], v[150:153], v[0:15]
	ds_read_b64_tr_b16 v[146:147], v145 offset:18432
	ds_read_b64_tr_b16 v[148:149], v145 offset:22528
	s_waitcnt lgkmcnt(12)
	v_mfma_f32_32x32x16_bf16 v[112:127], v[248:251], v[154:157], v[112:127]
	ds_read_b64_tr_b16 v[150:151], v145 offset:26624
	ds_read_b64_tr_b16 v[152:153], v145 offset:30720
	s_waitcnt lgkmcnt(12)
	v_mfma_f32_32x32x16_bf16 v[112:127], v[252:255], v[192:195], v[112:127]
	ds_read_b64_tr_b16 v[154:155], v145 offset:18944
	ds_read_b64_tr_b16 v[156:157], v145 offset:23040
	s_waitcnt lgkmcnt(12)
	v_mfma_f32_32x32x16_bf16 v[96:111], v[248:251], v[196:199], v[96:111]
	ds_read_b64_tr_b16 v[192:193], v145 offset:27136
	ds_read_b64_tr_b16 v[194:195], v145 offset:31232
	s_waitcnt lgkmcnt(12)
	v_mfma_f32_32x32x16_bf16 v[96:111], v[252:255], v[200:203], v[96:111]
	ds_read_b64_tr_b16 v[196:197], v145 offset:19456
	ds_read_b64_tr_b16 v[198:199], v145 offset:23552
	s_waitcnt lgkmcnt(12)
	v_mfma_f32_32x32x16_bf16 v[80:95], v[248:251], v[204:207], v[80:95]
	ds_read_b64_tr_b16 v[200:201], v145 offset:27648
	ds_read_b64_tr_b16 v[202:203], v145 offset:31744
	s_waitcnt lgkmcnt(12)
	v_mfma_f32_32x32x16_bf16 v[80:95], v[252:255], v[232:235], v[80:95]
	ds_read_b64_tr_b16 v[204:205], v145 offset:19968
	ds_read_b64_tr_b16 v[206:207], v145 offset:24064
	s_waitcnt lgkmcnt(12)
	v_mfma_f32_32x32x16_bf16 v[64:79], v[248:251], v[146:149], v[64:79]
	ds_read_b64_tr_b16 v[232:233], v145 offset:28160
	ds_read_b64_tr_b16 v[234:235], v145 offset:32256
	s_waitcnt lgkmcnt(12)
	v_mfma_f32_32x32x16_bf16 v[64:79], v[252:255], v[150:153], v[64:79]
	s_waitcnt lgkmcnt(10)
	v_mfma_f32_32x32x16_bf16 v[48:63], v[248:251], v[154:157], v[48:63]
	s_waitcnt lgkmcnt(8)
	v_mfma_f32_32x32x16_bf16 v[48:63], v[252:255], v[192:195], v[48:63]
	s_waitcnt lgkmcnt(6)
	v_mfma_f32_32x32x16_bf16 v[32:47], v[248:251], v[196:199], v[32:47]
	s_add_i32 s4, s76, 1
	s_cmp_lg_u32 s76, 2
	s_cselect_b32 s76, s4, 0
	s_add_i32 s4, s74, 1
	s_cmp_lg_u32 s74, 2
	s_cselect_b32 s74, s4, 0
	s_add_u32 s22, s22, 0x20000
	s_waitcnt lgkmcnt(4)
	v_mfma_f32_32x32x16_bf16 v[32:47], v[252:255], v[200:203], v[32:47]
	s_addc_u32 s23, s23, 0
	s_add_i32 s86, s86, 1
	s_cmp_eq_u32 s22, 0x800000
	s_waitcnt lgkmcnt(2)
	v_mfma_f32_32x32x16_bf16 v[16:31], v[248:251], v[204:207], v[16:31]
	s_waitcnt lgkmcnt(0)
	v_mfma_f32_32x32x16_bf16 v[16:31], v[252:255], v[232:235], v[16:31]
	s_cbranch_scc1 .LBB0_521
	v_mov_b32_e32 v239, v144
	s_cmp_eq_u32 s22, 0x7e0000
	s_mov_b64 s[4:5], -1
	s_cbranch_scc1 .LBB0_510

.LBB0_902:
	s_xor_b64 s[18:19], s[4:5], -1
	s_lshl_b64 s[4:5], s[0:1], 1
	s_add_u32 s22, s62, s4
	s_addc_u32 s23, s63, s5
	v_mov_b32_e32 v2, v208
	s_add_u32 s0, s64, s4
	s_addc_u32 s1, s65, s5
	v_readfirstlane_b32 s20, v2
	s_ashr_i32 s24, s20, 6
	s_and_b32 s20, s20, 0x3fffffc0
	s_lshl_b32 s20, s20, 2
	v_and_b32_e32 v219, 31, v2
	s_add_i32 s21, s20, 0
	s_lshl_b32 s20, s24, 5
	v_or_b32_e32 v0, s20, v219
	s_waitcnt lgkmcnt(0)
	v_ashrrev_i32_e32 v1, 31, v0
	v_bfe_u32 v218, v2, 5, 1
	v_lshlrev_b64 v[0:1], 11, v[0:1]
	v_lshl_add_u64 v[0:1], s[22:23], 0, v[0:1]
	v_lshlrev_b32_e32 v210, 4, v218
	v_lshl_add_u64 v[0:1], v[0:1], 0, v[210:211]
	global_load_dwordx4 v[160:163], v[0:1], off
	global_load_dwordx4 v[164:167], v[0:1], off offset:32
	global_load_dwordx4 v[168:171], v[0:1], off offset:64
	global_load_dwordx4 v[172:175], v[0:1], off offset:96
	global_load_dwordx4 v[176:179], v[0:1], off offset:128
	global_load_dwordx4 v[180:183], v[0:1], off offset:160
	global_load_dwordx4 v[184:187], v[0:1], off offset:192
	global_load_dwordx4 v[188:191], v[0:1], off offset:224
	s_lshl_b32 s22, s24, 3
	v_bfe_u32 v1, v2, 4, 2
	v_or_b32_e32 v0, s22, v1
	v_bitop3_b32 v4, v1, v2, 15 bitop3:0x78
	v_ashrrev_i32_e32 v1, 31, v0
	v_lshlrev_b64 v[212:213], 10, v[0:1]
	v_or_b32_e32 v0, 4, v0
	v_and_b32_e32 v3, 15, v2
	v_ashrrev_i32_e32 v1, 31, v0
	v_bitop3_b32 v3, v0, v3, 7 bitop3:0x6c
	s_and_b32 s25, s24, 1
	s_lshl_b32 s25, s25, 3
	v_xor_b32_e32 v4, s25, v4
	v_xor_b32_e32 v3, s25, v3
	v_lshlrev_b64 v[214:215], 10, v[0:1]
	v_bfe_u32 v0, v2, 2, 3
	v_bitop3_b32 v0, s22, -13, v0 bitop3:0xc8
	v_lshrrev_b32_e32 v1, 2, v2
	s_lshl_b32 s22, s24, 3
	v_and_b32_e32 v1, 4, v1
	s_and_b32 s22, s22, 8
	v_or3_b32 v0, v0, v1, s22
	s_add_i32 s21, s21, 0x24000
	v_ashrrev_i32_e32 v1, 31, v0
	v_lshlrev_b32_e32 v11, 3, v2
	s_lshl_b32 s22, s24, 11
	v_lshl_or_b32 v212, v4, 3, v212
	v_lshlrev_b64 v[216:217], 10, v[0:1]
	v_and_b32_e32 v0, 32, v2
	v_and_b32_e32 v1, 24, v11
	s_cmp_lg_u32 0, -1
	v_or3_b32 v216, v216, v1, v0
	v_lshlrev_b64 v[0:1], 1, v[212:213]
	s_cselect_b32 s23, 0, 0
	v_and_b32_e32 v10, 63, v2
	v_lshl_or_b32 v214, v3, 3, v214
	v_lshlrev_b32_e32 v12, 4, v2
	v_lshlrev_b32_e32 v13, 1, v2
	v_lshl_add_u64 v[2:3], s[0:1], 0, v[0:1]
	s_add_i32 s79, s22, s23
	s_mov_b32 s25, m0
	s_mov_b32 m0, s79
	s_nop 0
	global_load_lds_dwordx4 v[2:3], off
	s_mov_b32 m0, s25
	v_lshlrev_b64 v[2:3], 1, v[214:215]
	s_or_b32 s25, s22, 0x400
	v_lshl_add_u64 v[4:5], s[0:1], 0, v[2:3]
	s_add_i32 s81, s25, s23
	s_mov_b32 s84, m0
	s_mov_b32 m0, s81
	s_nop 0
	global_load_lds_dwordx4 v[4:5], off
	s_mov_b32 m0, s84
	s_lshl_b32 s24, s24, 12
	v_lshlrev_b64 v[4:5], 1, v[216:217]
	s_add_i32 s84, s23, 0xc000
	v_lshl_add_u64 v[6:7], s[14:15], 0, v[4:5]
	s_add_i32 s81, s24, s84
	s_mov_b32 s85, m0
	s_mov_b32 m0, s81
	s_nop 0
	global_load_lds_dwordx4 v[6:7], off
	s_mov_b32 m0, s85
	s_or_b32 s85, s24, 0x400
	s_add_i32 s86, s85, s84
	v_lshl_add_u64 v[8:9], v[6:7], 0, s[8:9]
	s_mov_b32 s87, m0
	s_mov_b32 m0, s86
	s_nop 0
	global_load_lds_dwordx4 v[8:9], off
	s_mov_b32 m0, s87
	s_or_b32 s86, s24, 0x800
	s_add_i32 s87, s86, s84
	v_lshl_add_u64 v[8:9], v[6:7], 0, s[10:11]
	s_mov_b32 s96, m0
	s_mov_b32 m0, s87
	s_nop 0
	global_load_lds_dwordx4 v[8:9], off
	s_mov_b32 m0, s96
	s_or_b32 s87, s24, 0xc00
	s_add_i32 s96, s87, s84
	s_add_u32 s0, s0, 0x20000
	v_lshl_add_u64 v[6:7], v[6:7], 0, s[12:13]
	s_mov_b32 s97, m0
	s_mov_b32 m0, s96
	s_nop 0
	global_load_lds_dwordx4 v[6:7], off
	s_mov_b32 m0, s97
	s_addc_u32 s1, s1, 0
	s_add_i32 s96, s23, 0x4000
	v_lshl_add_u64 v[0:1], s[0:1], 0, v[0:1]
	s_add_i32 s22, s22, s96
	s_mov_b32 s97, m0
	s_mov_b32 m0, s22
	s_nop 0
	global_load_lds_dwordx4 v[0:1], off
	s_mov_b32 m0, s97
	v_lshl_add_u64 v[0:1], s[0:1], 0, v[2:3]
	s_add_i32 s25, s25, s96
	s_mov_b32 s0, m0
	s_mov_b32 m0, s25
	s_nop 0
	global_load_lds_dwordx4 v[0:1], off
	s_mov_b32 m0, s0
	s_add_i32 s23, s23, 0x14000
	v_lshl_add_u64 v[0:1], s[16:17], 0, v[4:5]
	s_add_i32 s24, s24, s23
	s_mov_b32 s0, m0
	s_mov_b32 m0, s24
	s_nop 0
	global_load_lds_dwordx4 v[0:1], off
	s_mov_b32 m0, s0
	v_lshl_add_u64 v[2:3], v[0:1], 0, s[8:9]
	s_add_i32 s85, s85, s23
	s_mov_b32 s0, m0
	s_mov_b32 m0, s85
	s_nop 0
	global_load_lds_dwordx4 v[2:3], off
	s_mov_b32 m0, s0
	v_lshl_add_u64 v[2:3], v[0:1], 0, s[10:11]
	s_add_i32 s86, s86, s23
	s_mov_b32 s0, m0
	s_mov_b32 m0, s86
	s_nop 0
	global_load_lds_dwordx4 v[2:3], off
	s_mov_b32 m0, s0
	v_lshl_add_u64 v[0:1], v[0:1], 0, s[12:13]
	s_add_i32 s87, s87, s23
	s_mov_b32 s0, m0
	s_mov_b32 m0, s87
	s_nop 0
	global_load_lds_dwordx4 v[0:1], off
	s_mov_b32 m0, s0
	v_and_b32_e32 v0, 0x118, v11
	v_and_b32_e32 v14, 0xc0, v12
	s_movk_i32 s0, 0x70
	v_and_or_b32 v0, v13, 32, v0
	v_and_b32_e32 v1, 0x70, v12
	v_bitop3_b32 v221, v210, v12, s0 bitop3:0x78
	s_movk_i32 s0, 0xc0
	v_add3_u32 v230, v14, s84, v0
	v_mov_b32_e32 v14, v211
	v_mov_b32_e32 v15, v211
	v_bitop3_b32 v222, v210, v1, 32 bitop3:0x36
	v_bitop3_b32 v223, v210, v1, 64 bitop3:0x36
	v_bitop3_b32 v225, v210, v1, s38 bitop3:0x36
	v_bitop3_b32 v226, v210, v1, s39 bitop3:0x36
	v_bitop3_b32 v227, v210, v1, s40 bitop3:0x36
	v_bitop3_b32 v228, v210, v1, s0 bitop3:0x36
	v_bitop3_b32 v229, v210, v1, s41 bitop3:0x36
	v_and_b32_e32 v236, 0x80, v12
	v_xor_b32_e32 v221, v236, v221
	v_xor_b32_e32 v222, v236, v222
	v_xor_b32_e32 v223, v236, v223
	v_xor_b32_e32 v225, v236, v225
	v_xor_b32_e32 v226, v236, v226
	v_xor_b32_e32 v227, v236, v227
	v_xor_b32_e32 v228, v236, v228
	v_xor_b32_e32 v229, v236, v229
	v_cmp_gt_u32_e64 s[0:1], 32, v10
	s_add_u32 s84, s74, s4
	v_mov_b32_e32 v0, v211
	v_mov_b32_e32 v1, v211
	v_mov_b32_e32 v2, v211
	v_mov_b32_e32 v3, v211
	v_mov_b32_e32 v4, v211
	v_mov_b32_e32 v5, v211
	v_mov_b32_e32 v6, v211
	v_mov_b32_e32 v7, v211
	v_mov_b32_e32 v8, v211
	v_mov_b32_e32 v9, v211
	v_mov_b32_e32 v10, v211
	v_mov_b32_e32 v11, v211
	v_mov_b32_e32 v12, v211
	v_mov_b32_e32 v13, v211
	v_mov_b64_e32 v[126:127], v[14:15]
	v_mov_b64_e32 v[110:111], v[14:15]
	v_mov_b64_e32 v[94:95], v[14:15]
	v_mov_b64_e32 v[78:79], v[14:15]
	v_mov_b64_e32 v[62:63], v[14:15]
	v_mov_b64_e32 v[46:47], v[14:15]
	v_mov_b64_e32 v[30:31], v[14:15]
	s_mov_b32 s78, 2
	s_mov_b32 s80, 0
	v_lshlrev_b32_e32 v220, 8, v219
	v_lshl_add_u32 v224, v219, 2, s21
	s_addc_u32 s85, s75, s5
	v_mov_b32_e32 v232, 0
	v_mov_b32_e32 v239, 0
	v_mov_b32_e32 v231, 0xf149f2ca
	s_mov_b64 s[22:23], 0
	v_mov_b64_e32 v[124:125], v[12:13]
	v_mov_b64_e32 v[122:123], v[10:11]
	v_mov_b64_e32 v[120:121], v[8:9]
	v_mov_b64_e32 v[118:119], v[6:7]
	v_mov_b64_e32 v[116:117], v[4:5]
	v_mov_b64_e32 v[114:115], v[2:3]
	v_mov_b64_e32 v[112:113], v[0:1]
	v_mov_b64_e32 v[108:109], v[12:13]
	v_mov_b64_e32 v[106:107], v[10:11]
	v_mov_b64_e32 v[104:105], v[8:9]
	v_mov_b64_e32 v[102:103], v[6:7]
	v_mov_b64_e32 v[100:101], v[4:5]
	v_mov_b64_e32 v[98:99], v[2:3]
	v_mov_b64_e32 v[96:97], v[0:1]
	v_mov_b64_e32 v[92:93], v[12:13]
	v_mov_b64_e32 v[90:91], v[10:11]
	v_mov_b64_e32 v[88:89], v[8:9]
	v_mov_b64_e32 v[86:87], v[6:7]
	v_mov_b64_e32 v[84:85], v[4:5]
	v_mov_b64_e32 v[82:83], v[2:3]
	v_mov_b64_e32 v[80:81], v[0:1]
	v_mov_b64_e32 v[76:77], v[12:13]
	v_mov_b64_e32 v[74:75], v[10:11]
	v_mov_b64_e32 v[72:73], v[8:9]
	v_mov_b64_e32 v[70:71], v[6:7]
	v_mov_b64_e32 v[68:69], v[4:5]
	v_mov_b64_e32 v[66:67], v[2:3]
	v_mov_b64_e32 v[64:65], v[0:1]
	v_mov_b64_e32 v[60:61], v[12:13]
	v_mov_b64_e32 v[58:59], v[10:11]
	v_mov_b64_e32 v[56:57], v[8:9]
	v_mov_b64_e32 v[54:55], v[6:7]
	v_mov_b64_e32 v[52:53], v[4:5]
	v_mov_b64_e32 v[50:51], v[2:3]
	v_mov_b64_e32 v[48:49], v[0:1]
	v_mov_b64_e32 v[44:45], v[12:13]
	v_mov_b64_e32 v[42:43], v[10:11]
	v_mov_b64_e32 v[40:41], v[8:9]
	v_mov_b64_e32 v[38:39], v[6:7]
	v_mov_b64_e32 v[36:37], v[4:5]
	v_mov_b64_e32 v[34:35], v[2:3]
	v_mov_b64_e32 v[32:33], v[0:1]
	v_mov_b64_e32 v[28:29], v[12:13]
	v_mov_b64_e32 v[26:27], v[10:11]
	v_mov_b64_e32 v[24:25], v[8:9]
	v_mov_b64_e32 v[22:23], v[6:7]
	v_mov_b64_e32 v[20:21], v[4:5]
	v_mov_b64_e32 v[18:19], v[2:3]
	v_mov_b64_e32 v[16:17], v[0:1]
	s_mov_b32 s86, 0
	s_cmp_eq_u32 s22, 0x7e0000
	s_mov_b64 s[4:5], -1
	s_cbranch_scc0 .LBB0_912

.LBB0_910:
	v_cndmask_b32_e64 v231, v234, v231, s[4:5]
	v_mul_f32_e32 v192, 0xbe0293ee, v231
	v_fmamk_f32 v144, v144, 0x3e0293ee, v192
	v_fmamk_f32 v145, v145, 0x3e0293ee, v192
	v_fmamk_f32 v146, v146, 0x3e0293ee, v192
	v_fmamk_f32 v147, v147, 0x3e0293ee, v192
	v_fmamk_f32 v148, v148, 0x3e0293ee, v192
	v_fmamk_f32 v149, v149, 0x3e0293ee, v192
	v_fmamk_f32 v150, v150, 0x3e0293ee, v192
	v_fmamk_f32 v151, v151, 0x3e0293ee, v192
	v_fmamk_f32 v152, v152, 0x3e0293ee, v192
	v_fmamk_f32 v153, v153, 0x3e0293ee, v192
	v_fmamk_f32 v154, v154, 0x3e0293ee, v192
	v_fmamk_f32 v155, v155, 0x3e0293ee, v192
	v_fmamk_f32 v156, v156, 0x3e0293ee, v192
	v_fmamk_f32 v157, v157, 0x3e0293ee, v192
	v_fmamk_f32 v158, v158, 0x3e0293ee, v192
	v_fmamk_f32 v159, v159, 0x3e0293ee, v192
	v_fmamk_f32 v128, v128, 0x3e0293ee, v192
	v_fmamk_f32 v129, v129, 0x3e0293ee, v192
	v_fmamk_f32 v130, v130, 0x3e0293ee, v192
	v_fmamk_f32 v131, v131, 0x3e0293ee, v192
	v_fmamk_f32 v132, v132, 0x3e0293ee, v192
	v_fmamk_f32 v133, v133, 0x3e0293ee, v192
	v_fmamk_f32 v134, v134, 0x3e0293ee, v192
	v_fmamk_f32 v135, v135, 0x3e0293ee, v192
	v_fmamk_f32 v136, v136, 0x3e0293ee, v192
	v_fmamk_f32 v137, v137, 0x3e0293ee, v192
	v_fmamk_f32 v138, v138, 0x3e0293ee, v192
	v_fmamk_f32 v139, v139, 0x3e0293ee, v192
	v_fmamk_f32 v140, v140, 0x3e0293ee, v192
	v_fmamk_f32 v141, v141, 0x3e0293ee, v192
	v_fmamk_f32 v142, v142, 0x3e0293ee, v192
	v_fmamk_f32 v143, v143, 0x3e0293ee, v192
	v_exp_f32_e32 v144, v144
	v_exp_f32_e32 v145, v145
	v_exp_f32_e32 v146, v146
	v_exp_f32_e32 v147, v147
	v_exp_f32_e32 v148, v148
	v_exp_f32_e32 v149, v149
	v_exp_f32_e32 v150, v150
	v_exp_f32_e32 v151, v151
	v_exp_f32_e32 v152, v152
	v_exp_f32_e32 v153, v153
	v_exp_f32_e32 v154, v154
	v_exp_f32_e32 v155, v155
	v_exp_f32_e32 v156, v156
	v_exp_f32_e32 v157, v157
	v_exp_f32_e32 v158, v158
	v_exp_f32_e32 v159, v159
	v_add_f32_e32 v236, v144, v145
	v_add_f32_e32 v236, v146, v236
	v_add_f32_e32 v236, v147, v236
	v_add_f32_e32 v236, v148, v236
	v_add_f32_e32 v236, v149, v236
	v_add_f32_e32 v236, v150, v236
	v_add_f32_e32 v236, v151, v236
	v_add_f32_e32 v236, v152, v236
	v_add_f32_e32 v236, v153, v236
	v_add_f32_e32 v236, v154, v236
	v_add_f32_e32 v236, v155, v236
	v_add_f32_e32 v236, v156, v236
	v_add_f32_e32 v236, v157, v236
	v_add_f32_e32 v236, v158, v236
	v_add_f32_e32 v236, v159, v236
	v_cvt_pk_bf16_f32 v240, v144, v145
	v_cvt_pk_bf16_f32 v241, v146, v147
	v_cvt_pk_bf16_f32 v242, v148, v149
	v_cvt_pk_bf16_f32 v243, v150, v151
	v_cvt_pk_bf16_f32 v244, v152, v153
	v_cvt_pk_bf16_f32 v245, v154, v155
	v_cvt_pk_bf16_f32 v246, v156, v157
	v_cvt_pk_bf16_f32 v247, v158, v159
	v_mov_b32_e32 v158, v233
	v_lshl_add_u32 v145, s80, 15, v230
	ds_read_b64_tr_b16 v[146:147], v145 offset:0
	ds_read_b64_tr_b16 v[148:149], v145 offset:4096
	ds_read_b64_tr_b16 v[150:151], v145 offset:8192
	ds_read_b64_tr_b16 v[152:153], v145 offset:12288
	ds_read_b64_tr_b16 v[154:155], v145 offset:512
	ds_read_b64_tr_b16 v[156:157], v145 offset:4608
	ds_read_b64_tr_b16 v[192:193], v145 offset:8704
	ds_read_b64_tr_b16 v[194:195], v145 offset:12800
	ds_read_b64_tr_b16 v[196:197], v145 offset:1024
	ds_read_b64_tr_b16 v[198:199], v145 offset:5120
	ds_read_b64_tr_b16 v[200:201], v145 offset:9216
	ds_read_b64_tr_b16 v[202:203], v145 offset:13312
	ds_read_b64_tr_b16 v[204:205], v145 offset:1536
	ds_read_b64_tr_b16 v[206:207], v145 offset:5632
	s_waitcnt lgkmcnt(12)
	s_nop 0
	v_mfma_f32_32x32x16_bf16 v[0:15], v[240:243], v[146:149], v[0:15]
	ds_read_b64_tr_b16 v[232:233], v145 offset:9728
	ds_read_b64_tr_b16 v[234:235], v145 offset:13824
	v_exp_f32_e32 v128, v128
	v_exp_f32_e32 v129, v129
	v_exp_f32_e32 v130, v130
	s_waitcnt lgkmcnt(12)
	v_mfma_f32_32x32x16_bf16 v[0:15], v[244:247], v[150:153], v[0:15]
	ds_read_b64_tr_b16 v[146:147], v145 offset:2048
	ds_read_b64_tr_b16 v[148:149], v145 offset:6144
	v_exp_f32_e32 v131, v131
	v_exp_f32_e32 v132, v132
	s_waitcnt lgkmcnt(12)
	v_mfma_f32_32x32x16_bf16 v[112:127], v[240:243], v[154:157], v[112:127]
	ds_read_b64_tr_b16 v[150:151], v145 offset:10240
	ds_read_b64_tr_b16 v[152:153], v145 offset:14336
	v_exp_f32_e32 v133, v133
	v_exp_f32_e32 v134, v134
	v_exp_f32_e32 v135, v135
	s_waitcnt lgkmcnt(12)
	v_mfma_f32_32x32x16_bf16 v[112:127], v[244:247], v[192:195], v[112:127]
	ds_read_b64_tr_b16 v[154:155], v145 offset:2560
	ds_read_b64_tr_b16 v[156:157], v145 offset:6656
	v_exp_f32_e32 v136, v136
	v_exp_f32_e32 v137, v137
	s_waitcnt lgkmcnt(12)
	v_mfma_f32_32x32x16_bf16 v[96:111], v[240:243], v[196:199], v[96:111]
	ds_read_b64_tr_b16 v[192:193], v145 offset:10752
	ds_read_b64_tr_b16 v[194:195], v145 offset:14848
	v_exp_f32_e32 v138, v138
	v_exp_f32_e32 v139, v139
	v_exp_f32_e32 v140, v140
	s_waitcnt lgkmcnt(12)
	v_mfma_f32_32x32x16_bf16 v[96:111], v[244:247], v[200:203], v[96:111]
	ds_read_b64_tr_b16 v[196:197], v145 offset:3072
	ds_read_b64_tr_b16 v[198:199], v145 offset:7168
	v_exp_f32_e32 v141, v141
	v_exp_f32_e32 v142, v142
	s_waitcnt lgkmcnt(12)
	v_mfma_f32_32x32x16_bf16 v[80:95], v[240:243], v[204:207], v[80:95]
	ds_read_b64_tr_b16 v[200:201], v145 offset:11264
	ds_read_b64_tr_b16 v[202:203], v145 offset:15360
	v_exp_f32_e32 v143, v143
	v_add_f32_e32 v236, v128, v236
	v_add_f32_e32 v236, v129, v236
	s_waitcnt lgkmcnt(12)
	v_mfma_f32_32x32x16_bf16 v[80:95], v[244:247], v[232:235], v[80:95]
	ds_read_b64_tr_b16 v[204:205], v145 offset:3584
	ds_read_b64_tr_b16 v[206:207], v145 offset:7680
	v_add_f32_e32 v236, v130, v236
	v_add_f32_e32 v236, v131, v236
	s_waitcnt lgkmcnt(12)
	v_mfma_f32_32x32x16_bf16 v[64:79], v[240:243], v[146:149], v[64:79]
	ds_read_b64_tr_b16 v[232:233], v145 offset:11776
	ds_read_b64_tr_b16 v[234:235], v145 offset:15872
	v_add_f32_e32 v236, v132, v236
	v_add_f32_e32 v236, v133, v236
	v_add_f32_e32 v236, v134, v236
	s_waitcnt lgkmcnt(12)
	v_mfma_f32_32x32x16_bf16 v[64:79], v[244:247], v[150:153], v[64:79]
	ds_read_b64_tr_b16 v[146:147], v145 offset:16384
	ds_read_b64_tr_b16 v[148:149], v145 offset:20480
	v_add_f32_e32 v236, v135, v236
	v_add_f32_e32 v236, v136, v236
	s_waitcnt lgkmcnt(12)
	v_mfma_f32_32x32x16_bf16 v[48:63], v[240:243], v[154:157], v[48:63]
	ds_read_b64_tr_b16 v[150:151], v145 offset:24576
	ds_read_b64_tr_b16 v[152:153], v145 offset:28672
	v_add_f32_e32 v236, v137, v236
	v_add_f32_e32 v236, v138, v236
	v_add_f32_e32 v236, v139, v236
	s_waitcnt lgkmcnt(12)
	v_mfma_f32_32x32x16_bf16 v[48:63], v[244:247], v[192:195], v[48:63]
	ds_read_b64_tr_b16 v[154:155], v145 offset:16896
	ds_read_b64_tr_b16 v[156:157], v145 offset:20992
	v_add_f32_e32 v236, v140, v236
	v_add_f32_e32 v236, v141, v236
	s_waitcnt lgkmcnt(12)
	v_mfma_f32_32x32x16_bf16 v[32:47], v[240:243], v[196:199], v[32:47]
	ds_read_b64_tr_b16 v[192:193], v145 offset:25088
	ds_read_b64_tr_b16 v[194:195], v145 offset:29184
	v_add_f32_e32 v236, v142, v236
	v_add_f32_e32 v236, v143, v236
	v_cvt_pk_bf16_f32 v248, v128, v129
	s_waitcnt lgkmcnt(12)
	v_mfma_f32_32x32x16_bf16 v[32:47], v[244:247], v[200:203], v[32:47]
	ds_read_b64_tr_b16 v[196:197], v145 offset:17408
	ds_read_b64_tr_b16 v[198:199], v145 offset:21504
	v_cvt_pk_bf16_f32 v249, v130, v131
	v_cvt_pk_bf16_f32 v250, v132, v133
	s_waitcnt lgkmcnt(12)
	v_mfma_f32_32x32x16_bf16 v[16:31], v[240:243], v[204:207], v[16:31]
	ds_read_b64_tr_b16 v[200:201], v145 offset:25600
	ds_read_b64_tr_b16 v[202:203], v145 offset:29696
	v_cvt_pk_bf16_f32 v251, v134, v135
	v_cvt_pk_bf16_f32 v252, v136, v137
	v_cvt_pk_bf16_f32 v253, v138, v139
	s_waitcnt lgkmcnt(12)
	v_mfma_f32_32x32x16_bf16 v[16:31], v[244:247], v[232:235], v[16:31]
	ds_read_b64_tr_b16 v[204:205], v145 offset:17920
	ds_read_b64_tr_b16 v[206:207], v145 offset:22016
	v_cvt_pk_bf16_f32 v254, v140, v141
	v_cvt_pk_bf16_f32 v255, v142, v143
	s_waitcnt lgkmcnt(12)
	s_nop 1
	v_mfma_f32_32x32x16_bf16 v[0:15], v[248:251], v[146:149], v[0:15]
	ds_read_b64_tr_b16 v[232:233], v145 offset:26112
	ds_read_b64_tr_b16 v[234:235], v145 offset:30208
	v_mov_b32_e32 v237, v236
	s_nop 1
	v_permlane32_swap_b32_e32 v236, v237
	v_add_f32_e32 v144, v236, v237
	v_fmac_f32_e32 v144, v239, v158
	s_waitcnt lgkmcnt(12)
	v_mfma_f32_32x32x16_bf16 v[0:15], v[252:255], v[150:153], v[0:15]
	ds_read_b64_tr_b16 v[146:147], v145 offset:18432
	ds_read_b64_tr_b16 v[148:149], v145 offset:22528
	s_waitcnt lgkmcnt(12)
	v_mfma_f32_32x32x16_bf16 v[112:127], v[248:251], v[154:157], v[112:127]
	ds_read_b64_tr_b16 v[150:151], v145 offset:26624
	ds_read_b64_tr_b16 v[152:153], v145 offset:30720
	s_waitcnt lgkmcnt(12)
	v_mfma_f32_32x32x16_bf16 v[112:127], v[252:255], v[192:195], v[112:127]
	ds_read_b64_tr_b16 v[154:155], v145 offset:18944
	ds_read_b64_tr_b16 v[156:157], v145 offset:23040
	s_waitcnt lgkmcnt(12)
	v_mfma_f32_32x32x16_bf16 v[96:111], v[248:251], v[196:199], v[96:111]
	ds_read_b64_tr_b16 v[192:193], v145 offset:27136
	ds_read_b64_tr_b16 v[194:195], v145 offset:31232
	s_waitcnt lgkmcnt(12)
	v_mfma_f32_32x32x16_bf16 v[96:111], v[252:255], v[200:203], v[96:111]
	ds_read_b64_tr_b16 v[196:197], v145 offset:19456
	ds_read_b64_tr_b16 v[198:199], v145 offset:23552
	s_waitcnt lgkmcnt(12)
	v_mfma_f32_32x32x16_bf16 v[80:95], v[248:251], v[204:207], v[80:95]
	ds_read_b64_tr_b16 v[200:201], v145 offset:27648
	ds_read_b64_tr_b16 v[202:203], v145 offset:31744
	s_waitcnt lgkmcnt(12)
	v_mfma_f32_32x32x16_bf16 v[80:95], v[252:255], v[232:235], v[80:95]
	ds_read_b64_tr_b16 v[204:205], v145 offset:19968
	ds_read_b64_tr_b16 v[206:207], v145 offset:24064
	s_waitcnt lgkmcnt(12)
	v_mfma_f32_32x32x16_bf16 v[64:79], v[248:251], v[146:149], v[64:79]
	ds_read_b64_tr_b16 v[232:233], v145 offset:28160
	ds_read_b64_tr_b16 v[234:235], v145 offset:32256
	s_waitcnt lgkmcnt(12)
	v_mfma_f32_32x32x16_bf16 v[64:79], v[252:255], v[150:153], v[64:79]
	s_waitcnt lgkmcnt(10)
	v_mfma_f32_32x32x16_bf16 v[48:63], v[248:251], v[154:157], v[48:63]
	s_waitcnt lgkmcnt(8)
	v_mfma_f32_32x32x16_bf16 v[48:63], v[252:255], v[192:195], v[48:63]
	s_waitcnt lgkmcnt(6)
	v_mfma_f32_32x32x16_bf16 v[32:47], v[248:251], v[196:199], v[32:47]
	s_add_i32 s4, s80, 1
	s_cmp_lg_u32 s80, 2
	s_cselect_b32 s80, s4, 0
	s_add_i32 s4, s78, 1
	s_cmp_lg_u32 s78, 2
	s_cselect_b32 s78, s4, 0
	s_add_u32 s22, s22, 0x20000
	s_waitcnt lgkmcnt(4)
	v_mfma_f32_32x32x16_bf16 v[32:47], v[252:255], v[200:203], v[32:47]
	s_addc_u32 s23, s23, 0
	s_add_i32 s86, s86, 1
	s_cmp_eq_u32 s22, 0x800000
	s_waitcnt lgkmcnt(2)
	v_mfma_f32_32x32x16_bf16 v[16:31], v[248:251], v[204:207], v[16:31]
	s_waitcnt lgkmcnt(0)
	v_mfma_f32_32x32x16_bf16 v[16:31], v[252:255], v[232:235], v[16:31]
	s_cbranch_scc1 .LBB0_914
	v_mov_b32_e32 v239, v144
	s_cmp_eq_u32 s22, 0x7e0000
	s_mov_b64 s[4:5], -1
	s_cbranch_scc1 .LBB0_903
